# phase 0 filter: w1/w2/frequency rows of an item prefetched into registers at item start, MLP layer loops unrolled over the registers
# speedup vs baseline: 1.0515x; 1.0006x over previous
.Lflt_nostage:
	s_mul_i32 s1, s0, 0x900
	s_sub_i32 s38, s33, s1
	s_ashr_i32 s1, s0, 31
	s_mul_i32 s11, s0, 0x480000
	s_mul_hi_i32 s10, s0, 0x480000
	s_add_u32 s82, s2, s11
	s_addc_u32 s83, s56, s10
	s_lshl_b32 s10, s0, 6
	s_ashr_i32 s11, s10, 31
	s_lshl_b64 s[10:11], s[10:11], 2
	s_add_u32 s50, s18, s10
	s_addc_u32 s51, s19, s11
	s_lshl_b64 s[42:43], s[0:1], 14
	s_add_u32 s44, s22, s10
	s_mul_hi_i32 s49, s0, 0x2100
	s_mul_i32 s48, s0, 0x2100
	s_addc_u32 s45, s23, s11
	s_lshl_b64 s[40:41], s[0:1], 17
	s_lshl_b32 s0, s0, 7
	s_ashr_i32 s1, s0, 31
	s_lshl_b64 s[0:1], s[0:1], 2
	s_add_u32 s46, s26, s0
	s_addc_u32 s47, s27, s1
	v_mbcnt_lo_u32_b32 v99, -1, 0
	v_mbcnt_hi_u32_b32 v99, -1, v99
	v_lshlrev_b32_e32 v99, 2, v99
	v_lshl_add_u64 v[204:205], v[2:3], 0, s[48:49]
	s_mov_b64 s[0:1], 0x1000
	v_lshl_add_u64 v[206:207], v[204:205], 0, s[0:1]
	global_load_dword v104, v[204:205], off offset:-2560
	global_load_dword v105, v[204:205], off offset:-2304
	global_load_dword v106, v[204:205], off offset:-2048
	global_load_dword v107, v[204:205], off offset:-1792
	global_load_dword v108, v[204:205], off offset:-1536
	global_load_dword v109, v[204:205], off offset:-1280
	global_load_dword v110, v[204:205], off offset:-1024
	global_load_dword v111, v[204:205], off offset:-768
	global_load_dword v112, v[204:205], off offset:-512
	global_load_dword v113, v[204:205], off offset:-256
	global_load_dword v114, v[204:205], off offset:0
	global_load_dword v115, v[204:205], off offset:256
	global_load_dword v116, v[204:205], off offset:512
	global_load_dword v117, v[204:205], off offset:768
	global_load_dword v118, v[204:205], off offset:1024
	global_load_dword v119, v[204:205], off offset:1280
	global_load_dword v120, v[204:205], off offset:1536
	global_load_dword v121, v[204:205], off offset:1792
	global_load_dword v122, v[204:205], off offset:2048
	global_load_dword v123, v[204:205], off offset:2304
	global_load_dword v124, v[204:205], off offset:2560
	global_load_dword v125, v[204:205], off offset:2816
	global_load_dword v126, v[204:205], off offset:3072
	global_load_dword v127, v[204:205], off offset:3328
	global_load_dword v128, v[204:205], off offset:3584
	global_load_dword v129, v[204:205], off offset:3840
	global_load_dword v130, v[206:207], off offset:0
	global_load_dword v131, v[206:207], off offset:256
	global_load_dword v132, v[206:207], off offset:512
	global_load_dword v133, v[206:207], off offset:768
	global_load_dword v134, v[206:207], off offset:1024
	global_load_dword v135, v[206:207], off offset:1280
	global_load_dword v136, v[206:207], off offset:1536
	v_lshl_add_u64 v[204:205], v[4:5], 0, s[42:43]
	v_lshl_add_u64 v[206:207], v[204:205], 0, s[0:1]
	global_load_dword v140, v[204:205], off offset:-1792
	global_load_dword v141, v[204:205], off offset:-1536
	global_load_dword v142, v[204:205], off offset:-1280
	global_load_dword v143, v[204:205], off offset:-1024
	global_load_dword v144, v[204:205], off offset:-768
	global_load_dword v145, v[204:205], off offset:-512
	global_load_dword v146, v[204:205], off offset:-256
	global_load_dword v147, v[204:205], off offset:0
	global_load_dword v148, v[204:205], off offset:256
	global_load_dword v149, v[204:205], off offset:512
	global_load_dword v150, v[204:205], off offset:768
	global_load_dword v151, v[204:205], off offset:1024
	global_load_dword v152, v[204:205], off offset:1280
	global_load_dword v153, v[204:205], off offset:1536
	global_load_dword v154, v[204:205], off offset:1792
	global_load_dword v155, v[204:205], off offset:2048
	global_load_dword v156, v[204:205], off offset:2304
	global_load_dword v157, v[204:205], off offset:2560
	global_load_dword v158, v[204:205], off offset:2816
	global_load_dword v159, v[204:205], off offset:3072
	global_load_dword v160, v[204:205], off offset:3328
	global_load_dword v161, v[204:205], off offset:3584
	global_load_dword v162, v[204:205], off offset:3840
	global_load_dword v163, v[206:207], off offset:0
	global_load_dword v164, v[206:207], off offset:256
	global_load_dword v165, v[206:207], off offset:512
	global_load_dword v166, v[206:207], off offset:768
	global_load_dword v167, v[206:207], off offset:1024
	global_load_dword v168, v[206:207], off offset:1280
	global_load_dword v169, v[206:207], off offset:1536
	global_load_dword v170, v[206:207], off offset:1792
	global_load_dword v171, v[206:207], off offset:2048
	global_load_dword v172, v[206:207], off offset:2304
	global_load_dword v173, v[206:207], off offset:2560
	global_load_dword v174, v[206:207], off offset:2816
	global_load_dword v175, v[206:207], off offset:3072
	global_load_dword v176, v[206:207], off offset:3328
	global_load_dword v177, v[206:207], off offset:3584
	global_load_dword v178, v[206:207], off offset:3840
	s_mov_b64 s[0:1], 0x2000
	v_lshl_add_u64 v[204:205], v[204:205], 0, s[0:1]
	v_lshl_add_u64 v[206:207], v[206:207], 0, s[0:1]
	global_load_dword v179, v[204:205], off offset:0
	global_load_dword v180, v[204:205], off offset:256
	global_load_dword v181, v[204:205], off offset:512
	global_load_dword v182, v[204:205], off offset:768
	global_load_dword v183, v[204:205], off offset:1024
	global_load_dword v184, v[204:205], off offset:1280
	global_load_dword v185, v[204:205], off offset:1536
	global_load_dword v186, v[204:205], off offset:1792
	global_load_dword v187, v[204:205], off offset:2048
	global_load_dword v188, v[204:205], off offset:2304
	global_load_dword v189, v[204:205], off offset:2560
	global_load_dword v190, v[204:205], off offset:2816
	global_load_dword v191, v[204:205], off offset:3072
	global_load_dword v192, v[204:205], off offset:3328
	global_load_dword v193, v[204:205], off offset:3584
	global_load_dword v194, v[204:205], off offset:3840
	global_load_dword v195, v[206:207], off offset:0
	global_load_dword v196, v[206:207], off offset:256
	global_load_dword v197, v[206:207], off offset:512
	global_load_dword v198, v[206:207], off offset:768
	global_load_dword v199, v[206:207], off offset:1024
	global_load_dword v200, v[206:207], off offset:1280
	global_load_dword v201, v[206:207], off offset:1536
	global_load_dword v202, v[206:207], off offset:1792
	global_load_dword v203, v[206:207], off offset:2048
	global_load_dword v137, v99, s[46:47]
	global_load_dword v138, v99, s[46:47] offset:256
	s_cmpk_gt_i32 s38, 0xff
	s_mov_b64 s[0:1], -1
	s_cbranch_scc0 .LBB0_89
	s_add_i32 s0, s38, 0xffffff00
	v_cvt_f32_u32_e32 v0, s0
	v_div_scale_f32 v8, s[10:11], s61, s61, v0
	v_rcp_f32_e32 v9, v8
	v_div_scale_f32 v10, vcc, v0, s61, v0
	v_fma_f32 v11, -v8, v9, 1.0
	v_fmac_f32_e32 v9, v11, v9
	v_mul_f32_e32 v11, v10, v9
	v_fma_f32 v12, -v8, v11, v10
	v_fmac_f32_e32 v11, v12, v9
	v_fma_f32 v8, -v8, v11, v10
	v_div_fmas_f32 v8, v8, v9, v11
	v_div_fixup_f32 v35, v8, s61, v0
	v_cndmask_b32_e64 v10, 0, v35, s[8:9]
	s_and_saveexec_b64 s[52:53], s[6:7]
	s_cbranch_execz .LBB0_72
	v_mul_f32_e32 v0, 0x3b490fdb, v0
	v_mul_f32_e32 v8, v18, v0
	v_cmp_ngt_f32_e32 vcc, s62, v8
	s_and_saveexec_b64 s[10:11], s[4:5]
	s_xor_b64 s[54:55], exec, s[10:11]
	s_cbranch_execz .LBB0_65
	s_and_saveexec_b64 s[10:11], vcc
	s_xor_b64 s[58:59], exec, s[10:11]
	s_cbranch_execz .LBB0_62
	v_lshrrev_b32_e32 v0, 23, v8
	v_add_u32_e32 v0, 0xffffff88, v0
	v_cmp_lt_u32_e64 s[10:11], 63, v0
	s_nop 1
	v_cndmask_b32_e64 v9, 0, v28, s[10:11]
	v_add_u32_e32 v0, v9, v0
	v_cmp_lt_u32_e64 s[12:13], 31, v0
	s_nop 1
	v_cndmask_b32_e64 v9, 0, v29, s[12:13]
	v_add_u32_e32 v0, v9, v0
	v_cmp_lt_u32_e64 s[14:15], 31, v0
	s_nop 1
	v_cndmask_b32_e64 v9, 0, v29, s[14:15]
	v_add_u32_e32 v9, v9, v0
	v_and_b32_e32 v0, 0x7fffff, v8
	v_or_b32_e32 v40, 0x800000, v0
	v_mad_u64_u32 v[10:11], s[16:17], v40, s63, 0
	v_mov_b32_e32 v0, v11
	v_mad_u64_u32 v[12:13], s[16:17], v40, s64, v[0:1]
	v_mov_b32_e32 v0, v13
	v_mad_u64_u32 v[14:15], s[16:17], v40, s65, v[0:1]
	v_mov_b32_e32 v0, v15
	v_mad_u64_u32 v[16:17], s[16:17], v40, s66, v[0:1]
	v_mov_b32_e32 v0, v17
	v_mad_u64_u32 v[36:37], s[16:17], v40, s67, v[0:1]
	v_mov_b32_e32 v0, v37
	v_mad_u64_u32 v[38:39], s[16:17], v40, s73, v[0:1]
	v_mov_b32_e32 v0, v39
	v_mad_u64_u32 v[40:41], s[16:17], v40, s69, v[0:1]
	v_cndmask_b32_e64 v11, v38, v16, s[10:11]
	v_cndmask_b32_e64 v0, v40, v36, s[10:11]
	v_cndmask_b32_e64 v15, v41, v38, s[10:11]
	v_cndmask_b32_e64 v13, v0, v11, s[12:13]
	v_cndmask_b32_e64 v0, v15, v0, s[12:13]
	v_cndmask_b32_e64 v15, v36, v14, s[10:11]
	v_cndmask_b32_e64 v11, v11, v15, s[12:13]
	v_sub_u32_e32 v17, 32, v9
	v_cmp_eq_u32_e64 s[16:17], 0, v9
	v_cndmask_b32_e64 v9, v16, v12, s[10:11]
	v_cndmask_b32_e64 v0, v0, v13, s[14:15]
	v_cndmask_b32_e64 v13, v13, v11, s[14:15]
	v_cndmask_b32_e64 v12, v15, v9, s[12:13]
	v_alignbit_b32 v36, v0, v13, v17
	v_cndmask_b32_e64 v11, v11, v12, s[14:15]
	v_cndmask_b32_e64 v0, v36, v0, s[16:17]
	v_alignbit_b32 v15, v13, v11, v17
	v_cndmask_b32_e64 v10, v14, v10, s[10:11]
	v_cndmask_b32_e64 v13, v15, v13, s[16:17]
	v_bfe_u32 v36, v0, 29, 1
	v_cndmask_b32_e64 v9, v9, v10, s[12:13]
	v_alignbit_b32 v15, v0, v13, 30
	v_sub_u32_e32 v37, 0, v36
	v_cndmask_b32_e64 v9, v12, v9, s[14:15]
	v_xor_b32_e32 v15, v15, v37
	v_alignbit_b32 v10, v11, v9, v17
	v_cndmask_b32_e64 v10, v10, v11, s[16:17]
	v_ffbh_u32_e32 v12, v15
	v_alignbit_b32 v11, v13, v10, 30
	v_min_u32_e32 v12, 32, v12
	v_alignbit_b32 v9, v10, v9, 30
	v_xor_b32_e32 v11, v11, v37
	v_sub_u32_e32 v13, 31, v12
	v_xor_b32_e32 v9, v9, v37
	v_alignbit_b32 v14, v15, v11, v13
	v_alignbit_b32 v9, v11, v9, v13
	v_alignbit_b32 v10, v14, v9, 9
	v_ffbh_u32_e32 v11, v10
	v_min_u32_e32 v11, 32, v11
	v_lshrrev_b32_e32 v16, 29, v0
	v_not_b32_e32 v13, v11
	v_alignbit_b32 v9, v10, v9, v13
	v_lshlrev_b32_e32 v10, 31, v16
	v_or_b32_e32 v13, 0x33000000, v10
	v_add_lshl_u32 v11, v11, v12, 23
	v_lshrrev_b32_e32 v9, 9, v9
	v_sub_u32_e32 v11, v13, v11
	v_or_b32_e32 v10, 0.5, v10
	v_lshlrev_b32_e32 v12, 23, v12
	v_or_b32_e32 v9, v11, v9
	v_lshrrev_b32_e32 v11, 9, v14
	v_sub_u32_e32 v10, v10, v12
	v_or_b32_e32 v10, v11, v10
	v_mul_f32_e32 v11, 0x3fc90fda, v10
	v_fma_f32 v12, v10, s70, -v11
	v_fmac_f32_e32 v12, 0x33a22168, v10
	v_fmac_f32_e32 v12, 0x3fc90fda, v9
	v_lshrrev_b32_e32 v0, 30, v0
	v_add_f32_e32 v9, v11, v12
	v_add_u32_e32 v0, v36, v0

.LBB0_72:
	s_or_b64 exec, exec, s[52:53]
	v_lshlrev_b32_e32 v0, 2, v26
	global_load_dword v11, v0, s[50:51]
	s_mov_b32 s1, 0
	v_lshl_add_u64 v[8:9], v[2:3], 0, s[48:49]
	s_waitcnt vmcnt(0)
	ds_bpermute_b32 v208, v33, v10 offset:0
	ds_bpermute_b32 v209, v33, v10 offset:4
	ds_bpermute_b32 v210, v33, v10 offset:8
	ds_bpermute_b32 v211, v33, v10 offset:12
	ds_bpermute_b32 v212, v33, v10 offset:16
	ds_bpermute_b32 v213, v33, v10 offset:20
	ds_bpermute_b32 v214, v33, v10 offset:24
	ds_bpermute_b32 v215, v33, v10 offset:28
	ds_bpermute_b32 v216, v33, v10 offset:32
	ds_bpermute_b32 v217, v33, v10 offset:36
	ds_bpermute_b32 v218, v33, v10 offset:40
	s_waitcnt lgkmcnt(10)
	v_fmac_f32_e32 v11, v104, v208
	s_waitcnt lgkmcnt(9)
	v_fmac_f32_e32 v11, v105, v209
	s_waitcnt lgkmcnt(8)
	v_fmac_f32_e32 v11, v106, v210
	s_waitcnt lgkmcnt(7)
	v_fmac_f32_e32 v11, v107, v211
	s_waitcnt lgkmcnt(6)
	v_fmac_f32_e32 v11, v108, v212
	s_waitcnt lgkmcnt(5)
	v_fmac_f32_e32 v11, v109, v213
	s_waitcnt lgkmcnt(4)
	v_fmac_f32_e32 v11, v110, v214
	s_waitcnt lgkmcnt(3)
	v_fmac_f32_e32 v11, v111, v215
	s_waitcnt lgkmcnt(2)
	v_fmac_f32_e32 v11, v112, v216
	s_waitcnt lgkmcnt(1)
	v_fmac_f32_e32 v11, v113, v217
	s_waitcnt lgkmcnt(0)
	v_fmac_f32_e32 v11, v114, v218
	ds_bpermute_b32 v208, v33, v10 offset:44
	ds_bpermute_b32 v209, v33, v10 offset:48
	ds_bpermute_b32 v210, v33, v10 offset:52
	ds_bpermute_b32 v211, v33, v10 offset:56
	ds_bpermute_b32 v212, v33, v10 offset:60
	ds_bpermute_b32 v213, v33, v10 offset:64
	ds_bpermute_b32 v214, v33, v10 offset:68
	ds_bpermute_b32 v215, v33, v10 offset:72
	ds_bpermute_b32 v216, v33, v10 offset:76
	ds_bpermute_b32 v217, v33, v10 offset:80
	ds_bpermute_b32 v218, v33, v10 offset:84
	s_waitcnt lgkmcnt(10)
	v_fmac_f32_e32 v11, v115, v208
	s_waitcnt lgkmcnt(9)
	v_fmac_f32_e32 v11, v116, v209
	s_waitcnt lgkmcnt(8)
	v_fmac_f32_e32 v11, v117, v210
	s_waitcnt lgkmcnt(7)
	v_fmac_f32_e32 v11, v118, v211
	s_waitcnt lgkmcnt(6)
	v_fmac_f32_e32 v11, v119, v212
	s_waitcnt lgkmcnt(5)
	v_fmac_f32_e32 v11, v120, v213
	s_waitcnt lgkmcnt(4)
	v_fmac_f32_e32 v11, v121, v214
	s_waitcnt lgkmcnt(3)
	v_fmac_f32_e32 v11, v122, v215
	s_waitcnt lgkmcnt(2)
	v_fmac_f32_e32 v11, v123, v216
	s_waitcnt lgkmcnt(1)
	v_fmac_f32_e32 v11, v124, v217
	s_waitcnt lgkmcnt(0)
	v_fmac_f32_e32 v11, v125, v218
	ds_bpermute_b32 v208, v33, v10 offset:88
	ds_bpermute_b32 v209, v33, v10 offset:92
	ds_bpermute_b32 v210, v33, v10 offset:96
	ds_bpermute_b32 v211, v33, v10 offset:100
	ds_bpermute_b32 v212, v33, v10 offset:104
	ds_bpermute_b32 v213, v33, v10 offset:108
	ds_bpermute_b32 v214, v33, v10 offset:112
	ds_bpermute_b32 v215, v33, v10 offset:116
	ds_bpermute_b32 v216, v33, v10 offset:120
	ds_bpermute_b32 v217, v33, v10 offset:124
	ds_bpermute_b32 v218, v33, v10 offset:128
	s_waitcnt lgkmcnt(10)
	v_fmac_f32_e32 v11, v126, v208
	s_waitcnt lgkmcnt(9)
	v_fmac_f32_e32 v11, v127, v209
	s_waitcnt lgkmcnt(8)
	v_fmac_f32_e32 v11, v128, v210
	s_waitcnt lgkmcnt(7)
	v_fmac_f32_e32 v11, v129, v211
	s_waitcnt lgkmcnt(6)
	v_fmac_f32_e32 v11, v130, v212
	s_waitcnt lgkmcnt(5)
	v_fmac_f32_e32 v11, v131, v213
	s_waitcnt lgkmcnt(4)
	v_fmac_f32_e32 v11, v132, v214
	s_waitcnt lgkmcnt(3)
	v_fmac_f32_e32 v11, v133, v215
	s_waitcnt lgkmcnt(2)
	v_fmac_f32_e32 v11, v134, v216
	s_waitcnt lgkmcnt(1)
	v_fmac_f32_e32 v11, v135, v217
	s_waitcnt lgkmcnt(0)
	v_fmac_f32_e32 v11, v136, v218
	v_mov_b32_e32 v8, v137
	v_mul_f32_e32 v10, v11, v8
	v_and_b32_e32 v11, 0x7fffffff, v10
	v_cmp_nlt_f32_e64 s[10:11], |v10|, s62
	s_and_saveexec_b64 s[12:13], s[10:11]
	s_xor_b64 s[16:17], exec, s[12:13]
	s_cbranch_execz .LBB0_76
	v_lshrrev_b32_e32 v8, 23, v11
	v_add_u32_e32 v8, 0xffffff88, v8
	v_cmp_lt_u32_e32 vcc, 63, v8
	v_mov_b32_e32 v13, v1
	v_mov_b32_e32 v15, v1
	v_cndmask_b32_e32 v9, 0, v28, vcc
	v_add_u32_e32 v8, v9, v8
	v_cmp_lt_u32_e64 s[10:11], 31, v8
	v_mov_b32_e32 v17, v1
	v_mov_b32_e32 v37, v1
	v_cndmask_b32_e64 v9, 0, v29, s[10:11]
	v_add_u32_e32 v8, v9, v8
	v_cmp_lt_u32_e64 s[12:13], 31, v8
	v_mov_b32_e32 v39, v1
	v_mov_b32_e32 v41, v1
	v_cndmask_b32_e64 v9, 0, v29, s[12:13]
	v_add_u32_e32 v42, v9, v8
	v_and_b32_e32 v8, 0x7fffff, v11
	v_or_b32_e32 v43, 0x800000, v8
	v_mad_u64_u32 v[8:9], s[14:15], v43, s63, 0
	v_mov_b32_e32 v12, v9
	v_mad_u64_u32 v[12:13], s[14:15], v43, s64, v[12:13]
	v_mov_b32_e32 v14, v13
	v_mad_u64_u32 v[14:15], s[14:15], v43, s65, v[14:15]
	v_mov_b32_e32 v16, v15
	v_mad_u64_u32 v[16:17], s[14:15], v43, s66, v[16:17]
	v_mov_b32_e32 v36, v17
	v_mad_u64_u32 v[36:37], s[14:15], v43, s67, v[36:37]
	v_mov_b32_e32 v38, v37
	v_mad_u64_u32 v[38:39], s[14:15], v43, s73, v[38:39]
	v_mov_b32_e32 v40, v39
	v_mad_u64_u32 v[40:41], s[14:15], v43, s69, v[40:41]
	v_cndmask_b32_e32 v9, v38, v16, vcc
	v_cndmask_b32_e32 v13, v40, v36, vcc
	v_cndmask_b32_e32 v17, v41, v38, vcc
	v_cndmask_b32_e64 v15, v13, v9, s[10:11]
	v_cndmask_b32_e64 v13, v17, v13, s[10:11]
	v_cndmask_b32_e32 v17, v36, v14, vcc
	v_cndmask_b32_e64 v9, v9, v17, s[10:11]
	v_cndmask_b32_e32 v12, v16, v12, vcc
	v_cndmask_b32_e64 v13, v13, v15, s[12:13]
	v_cndmask_b32_e64 v15, v15, v9, s[12:13]
	v_sub_u32_e32 v36, 32, v42
	v_cndmask_b32_e64 v16, v17, v12, s[10:11]
	v_alignbit_b32 v37, v13, v15, v36
	v_cmp_eq_u32_e64 s[14:15], 0, v42
	v_cndmask_b32_e64 v9, v9, v16, s[12:13]
	v_alignbit_b32 v17, v15, v9, v36
	v_cndmask_b32_e64 v13, v37, v13, s[14:15]
	v_cndmask_b32_e32 v8, v14, v8, vcc
	v_cndmask_b32_e64 v15, v17, v15, s[14:15]
	v_bfe_u32 v38, v13, 29, 1
	v_cndmask_b32_e64 v8, v12, v8, s[10:11]
	v_alignbit_b32 v17, v13, v15, 30
	v_sub_u32_e32 v39, 0, v38
	v_cndmask_b32_e64 v8, v16, v8, s[12:13]
	v_xor_b32_e32 v17, v17, v39
	v_alignbit_b32 v12, v9, v8, v36
	v_cndmask_b32_e64 v9, v12, v9, s[14:15]
	v_ffbh_u32_e32 v14, v17
	v_alignbit_b32 v12, v15, v9, 30
	v_min_u32_e32 v14, 32, v14
	v_alignbit_b32 v8, v9, v8, 30
	v_xor_b32_e32 v12, v12, v39
	v_sub_u32_e32 v15, 31, v14
	v_xor_b32_e32 v8, v8, v39
	v_alignbit_b32 v16, v17, v12, v15
	v_alignbit_b32 v8, v12, v8, v15
	v_alignbit_b32 v9, v16, v8, 9
	v_ffbh_u32_e32 v12, v9
	v_min_u32_e32 v12, 32, v12
	v_lshrrev_b32_e32 v37, 29, v13
	v_not_b32_e32 v15, v12
	v_alignbit_b32 v8, v9, v8, v15
	v_lshlrev_b32_e32 v9, 31, v37
	v_or_b32_e32 v15, 0x33000000, v9
	v_add_lshl_u32 v12, v12, v14, 23
	v_lshrrev_b32_e32 v8, 9, v8
	v_sub_u32_e32 v12, v15, v12
	v_or_b32_e32 v9, 0.5, v9
	v_lshlrev_b32_e32 v14, 23, v14
	v_or_b32_e32 v8, v12, v8
	v_lshrrev_b32_e32 v12, 9, v16
	v_sub_u32_e32 v9, v9, v14
	v_or_b32_e32 v9, v12, v9
	v_mul_f32_e32 v12, 0x3fc90fda, v9
	v_fma_f32 v14, v9, s70, -v12
	v_fmac_f32_e32 v14, 0x33a22168, v9
	v_fmac_f32_e32 v14, 0x3fc90fda, v8
	v_lshrrev_b32_e32 v8, 30, v13
	v_add_f32_e32 v14, v12, v14
	v_add_u32_e32 v13, v38, v8
.LBB0_76:
	s_andn2_saveexec_b64 s[10:11], s[16:17]
	v_mul_f32_e64 v8, |v10|, s71
	v_rndne_f32_e32 v8, v8
	v_cvt_i32_f32_e32 v13, v8
	v_fma_f32 v14, v8, s72, |v10|
	v_fmac_f32_e32 v14, 0xb3a22168, v8
	v_fmac_f32_e32 v14, 0xa7c234c4, v8
	s_or_b64 exec, exec, s[10:11]
	global_load_dword v12, v0, s[44:45]
	v_mul_f32_e32 v15, v14, v14
	v_fmamk_f32 v16, v15, 0xb94c1982, v23
	v_fmaak_f32 v16, v15, v16, 0xbe2aaa9d
	v_mul_f32_e32 v16, v15, v16
	v_fmac_f32_e32 v14, v14, v16
	v_fmamk_f32 v16, v15, 0x37d75334, v25
	v_fmaak_f32 v16, v15, v16, 0x3d2aabf7
	v_fmaak_f32 v16, v15, v16, 0xbf000004
	v_fma_f32 v15, v15, v16, 1.0
	v_and_b32_e32 v16, 1, v13
	v_lshlrev_b32_e32 v13, 30, v13
	v_cmp_eq_u32_e32 vcc, 0, v16
	v_and_b32_e32 v13, 0x80000000, v13
	v_xor_b32_e32 v11, v11, v10
	v_cndmask_b32_e32 v14, v15, v14, vcc
	v_xor_b32_e32 v11, v11, v13
	v_xor_b32_e32 v11, v11, v14
	v_cmp_class_f32_e64 vcc, v10, s76
	v_lshl_add_u64 v[8:9], s[46:47], 0, v[0:1]
	s_mov_b32 s1, 0
	v_cndmask_b32_e32 v13, v31, v11, vcc
	v_lshl_add_u64 v[10:11], v[4:5], 0, s[42:43]
	s_waitcnt vmcnt(0)
	ds_bpermute_b32 v208, v33, v13 offset:0
	ds_bpermute_b32 v209, v33, v13 offset:4
	ds_bpermute_b32 v210, v33, v13 offset:8
	ds_bpermute_b32 v211, v33, v13 offset:12
	ds_bpermute_b32 v212, v33, v13 offset:16
	ds_bpermute_b32 v213, v33, v13 offset:20
	ds_bpermute_b32 v214, v33, v13 offset:24
	ds_bpermute_b32 v215, v33, v13 offset:28
	s_waitcnt lgkmcnt(7)
	v_fmac_f32_e32 v12, v140, v208
	s_waitcnt lgkmcnt(6)
	v_fmac_f32_e32 v12, v141, v209
	s_waitcnt lgkmcnt(5)
	v_fmac_f32_e32 v12, v142, v210
	s_waitcnt lgkmcnt(4)
	v_fmac_f32_e32 v12, v143, v211
	s_waitcnt lgkmcnt(3)
	v_fmac_f32_e32 v12, v144, v212
	s_waitcnt lgkmcnt(2)
	v_fmac_f32_e32 v12, v145, v213
	s_waitcnt lgkmcnt(1)
	v_fmac_f32_e32 v12, v146, v214
	s_waitcnt lgkmcnt(0)
	v_fmac_f32_e32 v12, v147, v215
	ds_bpermute_b32 v208, v33, v13 offset:32
	ds_bpermute_b32 v209, v33, v13 offset:36
	ds_bpermute_b32 v210, v33, v13 offset:40
	ds_bpermute_b32 v211, v33, v13 offset:44
	ds_bpermute_b32 v212, v33, v13 offset:48
	ds_bpermute_b32 v213, v33, v13 offset:52
	ds_bpermute_b32 v214, v33, v13 offset:56
	ds_bpermute_b32 v215, v33, v13 offset:60
	s_waitcnt lgkmcnt(7)
	v_fmac_f32_e32 v12, v148, v208
	s_waitcnt lgkmcnt(6)
	v_fmac_f32_e32 v12, v149, v209
	s_waitcnt lgkmcnt(5)
	v_fmac_f32_e32 v12, v150, v210
	s_waitcnt lgkmcnt(4)
	v_fmac_f32_e32 v12, v151, v211
	s_waitcnt lgkmcnt(3)
	v_fmac_f32_e32 v12, v152, v212
	s_waitcnt lgkmcnt(2)
	v_fmac_f32_e32 v12, v153, v213
	s_waitcnt lgkmcnt(1)
	v_fmac_f32_e32 v12, v154, v214
	s_waitcnt lgkmcnt(0)
	v_fmac_f32_e32 v12, v155, v215
	ds_bpermute_b32 v208, v33, v13 offset:64
	ds_bpermute_b32 v209, v33, v13 offset:68
	ds_bpermute_b32 v210, v33, v13 offset:72
	ds_bpermute_b32 v211, v33, v13 offset:76
	ds_bpermute_b32 v212, v33, v13 offset:80
	ds_bpermute_b32 v213, v33, v13 offset:84
	ds_bpermute_b32 v214, v33, v13 offset:88
	ds_bpermute_b32 v215, v33, v13 offset:92
	s_waitcnt lgkmcnt(7)
	v_fmac_f32_e32 v12, v156, v208
	s_waitcnt lgkmcnt(6)
	v_fmac_f32_e32 v12, v157, v209
	s_waitcnt lgkmcnt(5)
	v_fmac_f32_e32 v12, v158, v210
	s_waitcnt lgkmcnt(4)
	v_fmac_f32_e32 v12, v159, v211
	s_waitcnt lgkmcnt(3)
	v_fmac_f32_e32 v12, v160, v212
	s_waitcnt lgkmcnt(2)
	v_fmac_f32_e32 v12, v161, v213
	s_waitcnt lgkmcnt(1)
	v_fmac_f32_e32 v12, v162, v214
	s_waitcnt lgkmcnt(0)
	v_fmac_f32_e32 v12, v163, v215
	ds_bpermute_b32 v208, v33, v13 offset:96
	ds_bpermute_b32 v209, v33, v13 offset:100
	ds_bpermute_b32 v210, v33, v13 offset:104
	ds_bpermute_b32 v211, v33, v13 offset:108
	ds_bpermute_b32 v212, v33, v13 offset:112
	ds_bpermute_b32 v213, v33, v13 offset:116
	ds_bpermute_b32 v214, v33, v13 offset:120
	ds_bpermute_b32 v215, v33, v13 offset:124
	s_waitcnt lgkmcnt(7)
	v_fmac_f32_e32 v12, v164, v208
	s_waitcnt lgkmcnt(6)
	v_fmac_f32_e32 v12, v165, v209
	s_waitcnt lgkmcnt(5)
	v_fmac_f32_e32 v12, v166, v210
	s_waitcnt lgkmcnt(4)
	v_fmac_f32_e32 v12, v167, v211
	s_waitcnt lgkmcnt(3)
	v_fmac_f32_e32 v12, v168, v212
	s_waitcnt lgkmcnt(2)
	v_fmac_f32_e32 v12, v169, v213
	s_waitcnt lgkmcnt(1)
	v_fmac_f32_e32 v12, v170, v214
	s_waitcnt lgkmcnt(0)
	v_fmac_f32_e32 v12, v171, v215
	ds_bpermute_b32 v208, v33, v13 offset:128
	ds_bpermute_b32 v209, v33, v13 offset:132
	ds_bpermute_b32 v210, v33, v13 offset:136
	ds_bpermute_b32 v211, v33, v13 offset:140
	ds_bpermute_b32 v212, v33, v13 offset:144
	ds_bpermute_b32 v213, v33, v13 offset:148
	ds_bpermute_b32 v214, v33, v13 offset:152
	ds_bpermute_b32 v215, v33, v13 offset:156
	s_waitcnt lgkmcnt(7)
	v_fmac_f32_e32 v12, v172, v208
	s_waitcnt lgkmcnt(6)
	v_fmac_f32_e32 v12, v173, v209
	s_waitcnt lgkmcnt(5)
	v_fmac_f32_e32 v12, v174, v210
	s_waitcnt lgkmcnt(4)
	v_fmac_f32_e32 v12, v175, v211
	s_waitcnt lgkmcnt(3)
	v_fmac_f32_e32 v12, v176, v212
	s_waitcnt lgkmcnt(2)
	v_fmac_f32_e32 v12, v177, v213
	s_waitcnt lgkmcnt(1)
	v_fmac_f32_e32 v12, v178, v214
	s_waitcnt lgkmcnt(0)
	v_fmac_f32_e32 v12, v179, v215
	ds_bpermute_b32 v208, v33, v13 offset:160
	ds_bpermute_b32 v209, v33, v13 offset:164
	ds_bpermute_b32 v210, v33, v13 offset:168
	ds_bpermute_b32 v211, v33, v13 offset:172
	ds_bpermute_b32 v212, v33, v13 offset:176
	ds_bpermute_b32 v213, v33, v13 offset:180
	ds_bpermute_b32 v214, v33, v13 offset:184
	ds_bpermute_b32 v215, v33, v13 offset:188
	s_waitcnt lgkmcnt(7)
	v_fmac_f32_e32 v12, v180, v208
	s_waitcnt lgkmcnt(6)
	v_fmac_f32_e32 v12, v181, v209
	s_waitcnt lgkmcnt(5)
	v_fmac_f32_e32 v12, v182, v210
	s_waitcnt lgkmcnt(4)
	v_fmac_f32_e32 v12, v183, v211
	s_waitcnt lgkmcnt(3)
	v_fmac_f32_e32 v12, v184, v212
	s_waitcnt lgkmcnt(2)
	v_fmac_f32_e32 v12, v185, v213
	s_waitcnt lgkmcnt(1)
	v_fmac_f32_e32 v12, v186, v214
	s_waitcnt lgkmcnt(0)
	v_fmac_f32_e32 v12, v187, v215
	ds_bpermute_b32 v208, v33, v13 offset:192
	ds_bpermute_b32 v209, v33, v13 offset:196
	ds_bpermute_b32 v210, v33, v13 offset:200
	ds_bpermute_b32 v211, v33, v13 offset:204
	ds_bpermute_b32 v212, v33, v13 offset:208
	ds_bpermute_b32 v213, v33, v13 offset:212
	ds_bpermute_b32 v214, v33, v13 offset:216
	ds_bpermute_b32 v215, v33, v13 offset:220
	s_waitcnt lgkmcnt(7)
	v_fmac_f32_e32 v12, v188, v208
	s_waitcnt lgkmcnt(6)
	v_fmac_f32_e32 v12, v189, v209
	s_waitcnt lgkmcnt(5)
	v_fmac_f32_e32 v12, v190, v210
	s_waitcnt lgkmcnt(4)
	v_fmac_f32_e32 v12, v191, v211
	s_waitcnt lgkmcnt(3)
	v_fmac_f32_e32 v12, v192, v212
	s_waitcnt lgkmcnt(2)
	v_fmac_f32_e32 v12, v193, v213
	s_waitcnt lgkmcnt(1)
	v_fmac_f32_e32 v12, v194, v214
	s_waitcnt lgkmcnt(0)
	v_fmac_f32_e32 v12, v195, v215
	ds_bpermute_b32 v208, v33, v13 offset:224
	ds_bpermute_b32 v209, v33, v13 offset:228
	ds_bpermute_b32 v210, v33, v13 offset:232
	ds_bpermute_b32 v211, v33, v13 offset:236
	ds_bpermute_b32 v212, v33, v13 offset:240
	ds_bpermute_b32 v213, v33, v13 offset:244
	ds_bpermute_b32 v214, v33, v13 offset:248
	ds_bpermute_b32 v215, v33, v13 offset:252
	s_waitcnt lgkmcnt(7)
	v_fmac_f32_e32 v12, v196, v208
	s_waitcnt lgkmcnt(6)
	v_fmac_f32_e32 v12, v197, v209
	s_waitcnt lgkmcnt(5)
	v_fmac_f32_e32 v12, v198, v210
	s_waitcnt lgkmcnt(4)
	v_fmac_f32_e32 v12, v199, v211
	s_waitcnt lgkmcnt(3)
	v_fmac_f32_e32 v12, v200, v212
	s_waitcnt lgkmcnt(2)
	v_fmac_f32_e32 v12, v201, v213
	s_waitcnt lgkmcnt(1)
	v_fmac_f32_e32 v12, v202, v214
	s_waitcnt lgkmcnt(0)
	v_fmac_f32_e32 v12, v203, v215
	v_mov_b32_e32 v8, v138
	v_mul_f32_e32 v8, v12, v8
	v_and_b32_e32 v9, 0x7fffffff, v8
	v_cmp_nlt_f32_e64 s[10:11], |v8|, s62
	s_and_saveexec_b64 s[12:13], s[10:11]
	s_xor_b64 s[16:17], exec, s[12:13]
	s_cbranch_execz .LBB0_82
	v_lshrrev_b32_e32 v10, 23, v9
	v_add_u32_e32 v10, 0xffffff88, v10
	v_cmp_lt_u32_e32 vcc, 63, v10
	v_mov_b32_e32 v13, v1
	v_mov_b32_e32 v15, v1
	v_cndmask_b32_e32 v11, 0, v28, vcc
	v_add_u32_e32 v10, v11, v10
	v_cmp_lt_u32_e64 s[10:11], 31, v10
	v_mov_b32_e32 v17, v1
	v_mov_b32_e32 v37, v1
	v_cndmask_b32_e64 v11, 0, v29, s[10:11]
	v_add_u32_e32 v10, v11, v10
	v_cmp_lt_u32_e64 s[12:13], 31, v10
	v_mov_b32_e32 v39, v1
	v_mov_b32_e32 v41, v1
	v_cndmask_b32_e64 v11, 0, v29, s[12:13]
	v_add_u32_e32 v42, v11, v10
	v_and_b32_e32 v10, 0x7fffff, v9
	v_or_b32_e32 v43, 0x800000, v10
	v_mad_u64_u32 v[10:11], s[14:15], v43, s63, 0
	v_mov_b32_e32 v12, v11
	v_mad_u64_u32 v[12:13], s[14:15], v43, s64, v[12:13]
	v_mov_b32_e32 v14, v13
	v_mad_u64_u32 v[14:15], s[14:15], v43, s65, v[14:15]
	v_mov_b32_e32 v16, v15
	v_mad_u64_u32 v[16:17], s[14:15], v43, s66, v[16:17]
	v_mov_b32_e32 v36, v17
	v_mad_u64_u32 v[36:37], s[14:15], v43, s67, v[36:37]
	v_mov_b32_e32 v38, v37
	v_mad_u64_u32 v[38:39], s[14:15], v43, s73, v[38:39]
	v_mov_b32_e32 v40, v39
	v_mad_u64_u32 v[40:41], s[14:15], v43, s69, v[40:41]
	v_cndmask_b32_e32 v11, v38, v16, vcc
	v_cndmask_b32_e32 v13, v40, v36, vcc
	v_cndmask_b32_e32 v17, v41, v38, vcc
	v_cndmask_b32_e64 v15, v13, v11, s[10:11]
	v_cndmask_b32_e64 v13, v17, v13, s[10:11]
	v_cndmask_b32_e32 v17, v36, v14, vcc
	v_cndmask_b32_e64 v11, v11, v17, s[10:11]
	v_cndmask_b32_e32 v12, v16, v12, vcc
	v_cndmask_b32_e64 v13, v13, v15, s[12:13]
	v_cndmask_b32_e64 v15, v15, v11, s[12:13]
	v_sub_u32_e32 v36, 32, v42
	v_cndmask_b32_e64 v16, v17, v12, s[10:11]
	v_alignbit_b32 v37, v13, v15, v36
	v_cmp_eq_u32_e64 s[14:15], 0, v42
	v_cndmask_b32_e64 v11, v11, v16, s[12:13]
	v_alignbit_b32 v17, v15, v11, v36
	v_cndmask_b32_e64 v13, v37, v13, s[14:15]
	v_cndmask_b32_e32 v10, v14, v10, vcc
	v_cndmask_b32_e64 v15, v17, v15, s[14:15]
	v_bfe_u32 v38, v13, 29, 1
	v_cndmask_b32_e64 v10, v12, v10, s[10:11]
	v_alignbit_b32 v17, v13, v15, 30
	v_sub_u32_e32 v39, 0, v38
	v_cndmask_b32_e64 v10, v16, v10, s[12:13]
	v_xor_b32_e32 v17, v17, v39
	v_alignbit_b32 v12, v11, v10, v36
	v_cndmask_b32_e64 v11, v12, v11, s[14:15]
	v_ffbh_u32_e32 v14, v17
	v_alignbit_b32 v12, v15, v11, 30
	v_min_u32_e32 v14, 32, v14
	v_alignbit_b32 v10, v11, v10, 30
	v_xor_b32_e32 v12, v12, v39
	v_sub_u32_e32 v15, 31, v14
	v_xor_b32_e32 v10, v10, v39
	v_alignbit_b32 v16, v17, v12, v15
	v_alignbit_b32 v10, v12, v10, v15
	v_alignbit_b32 v11, v16, v10, 9
	v_ffbh_u32_e32 v12, v11
	v_min_u32_e32 v12, 32, v12
	v_lshrrev_b32_e32 v37, 29, v13
	v_not_b32_e32 v15, v12
	v_alignbit_b32 v10, v11, v10, v15
	v_lshlrev_b32_e32 v11, 31, v37
	v_or_b32_e32 v15, 0x33000000, v11
	v_add_lshl_u32 v12, v12, v14, 23
	v_lshrrev_b32_e32 v10, 9, v10
	v_sub_u32_e32 v12, v15, v12
	v_or_b32_e32 v11, 0.5, v11
	v_lshlrev_b32_e32 v14, 23, v14
	v_or_b32_e32 v10, v12, v10
	v_lshrrev_b32_e32 v12, 9, v16
	v_sub_u32_e32 v11, v11, v14
	v_or_b32_e32 v11, v12, v11
	v_mul_f32_e32 v12, 0x3fc90fda, v11
	v_fma_f32 v14, v11, s70, -v12
	v_fmac_f32_e32 v14, 0x33a22168, v11
	v_fmac_f32_e32 v14, 0x3fc90fda, v10
	v_lshrrev_b32_e32 v10, 30, v13
	v_add_f32_e32 v11, v12, v14
	v_add_u32_e32 v10, v38, v10

.LBB0_104:
	s_or_b64 exec, exec, s[16:17]
	v_lshlrev_b32_e32 v0, 2, v26
	global_load_dword v11, v0, s[50:51]
	s_mov_b32 s0, 0
	v_and_b32_e32 v36, 0x100, v32
	v_lshl_add_u64 v[8:9], v[2:3], 0, s[48:49]
	s_waitcnt vmcnt(0)
	ds_bpermute_b32 v208, v36, v10 offset:0
	ds_bpermute_b32 v209, v36, v10 offset:4
	ds_bpermute_b32 v210, v36, v10 offset:8
	ds_bpermute_b32 v211, v36, v10 offset:12
	ds_bpermute_b32 v212, v36, v10 offset:16
	ds_bpermute_b32 v213, v36, v10 offset:20
	ds_bpermute_b32 v214, v36, v10 offset:24
	ds_bpermute_b32 v215, v36, v10 offset:28
	ds_bpermute_b32 v216, v36, v10 offset:32
	ds_bpermute_b32 v217, v36, v10 offset:36
	ds_bpermute_b32 v218, v36, v10 offset:40
	s_waitcnt lgkmcnt(10)
	v_fmac_f32_e32 v11, v104, v208
	s_waitcnt lgkmcnt(9)
	v_fmac_f32_e32 v11, v105, v209
	s_waitcnt lgkmcnt(8)
	v_fmac_f32_e32 v11, v106, v210
	s_waitcnt lgkmcnt(7)
	v_fmac_f32_e32 v11, v107, v211
	s_waitcnt lgkmcnt(6)
	v_fmac_f32_e32 v11, v108, v212
	s_waitcnt lgkmcnt(5)
	v_fmac_f32_e32 v11, v109, v213
	s_waitcnt lgkmcnt(4)
	v_fmac_f32_e32 v11, v110, v214
	s_waitcnt lgkmcnt(3)
	v_fmac_f32_e32 v11, v111, v215
	s_waitcnt lgkmcnt(2)
	v_fmac_f32_e32 v11, v112, v216
	s_waitcnt lgkmcnt(1)
	v_fmac_f32_e32 v11, v113, v217
	s_waitcnt lgkmcnt(0)
	v_fmac_f32_e32 v11, v114, v218
	ds_bpermute_b32 v208, v36, v10 offset:44
	ds_bpermute_b32 v209, v36, v10 offset:48
	ds_bpermute_b32 v210, v36, v10 offset:52
	ds_bpermute_b32 v211, v36, v10 offset:56
	ds_bpermute_b32 v212, v36, v10 offset:60
	ds_bpermute_b32 v213, v36, v10 offset:64
	ds_bpermute_b32 v214, v36, v10 offset:68
	ds_bpermute_b32 v215, v36, v10 offset:72
	ds_bpermute_b32 v216, v36, v10 offset:76
	ds_bpermute_b32 v217, v36, v10 offset:80
	ds_bpermute_b32 v218, v36, v10 offset:84
	s_waitcnt lgkmcnt(10)
	v_fmac_f32_e32 v11, v115, v208
	s_waitcnt lgkmcnt(9)
	v_fmac_f32_e32 v11, v116, v209
	s_waitcnt lgkmcnt(8)
	v_fmac_f32_e32 v11, v117, v210
	s_waitcnt lgkmcnt(7)
	v_fmac_f32_e32 v11, v118, v211
	s_waitcnt lgkmcnt(6)
	v_fmac_f32_e32 v11, v119, v212
	s_waitcnt lgkmcnt(5)
	v_fmac_f32_e32 v11, v120, v213
	s_waitcnt lgkmcnt(4)
	v_fmac_f32_e32 v11, v121, v214
	s_waitcnt lgkmcnt(3)
	v_fmac_f32_e32 v11, v122, v215
	s_waitcnt lgkmcnt(2)
	v_fmac_f32_e32 v11, v123, v216
	s_waitcnt lgkmcnt(1)
	v_fmac_f32_e32 v11, v124, v217
	s_waitcnt lgkmcnt(0)
	v_fmac_f32_e32 v11, v125, v218
	ds_bpermute_b32 v208, v36, v10 offset:88
	ds_bpermute_b32 v209, v36, v10 offset:92
	ds_bpermute_b32 v210, v36, v10 offset:96
	ds_bpermute_b32 v211, v36, v10 offset:100
	ds_bpermute_b32 v212, v36, v10 offset:104
	ds_bpermute_b32 v213, v36, v10 offset:108
	ds_bpermute_b32 v214, v36, v10 offset:112
	ds_bpermute_b32 v215, v36, v10 offset:116
	ds_bpermute_b32 v216, v36, v10 offset:120
	ds_bpermute_b32 v217, v36, v10 offset:124
	ds_bpermute_b32 v218, v36, v10 offset:128
	s_waitcnt lgkmcnt(10)
	v_fmac_f32_e32 v11, v126, v208
	s_waitcnt lgkmcnt(9)
	v_fmac_f32_e32 v11, v127, v209
	s_waitcnt lgkmcnt(8)
	v_fmac_f32_e32 v11, v128, v210
	s_waitcnt lgkmcnt(7)
	v_fmac_f32_e32 v11, v129, v211
	s_waitcnt lgkmcnt(6)
	v_fmac_f32_e32 v11, v130, v212
	s_waitcnt lgkmcnt(5)
	v_fmac_f32_e32 v11, v131, v213
	s_waitcnt lgkmcnt(4)
	v_fmac_f32_e32 v11, v132, v214
	s_waitcnt lgkmcnt(3)
	v_fmac_f32_e32 v11, v133, v215
	s_waitcnt lgkmcnt(2)
	v_fmac_f32_e32 v11, v134, v216
	s_waitcnt lgkmcnt(1)
	v_fmac_f32_e32 v11, v135, v217
	s_waitcnt lgkmcnt(0)
	v_fmac_f32_e32 v11, v136, v218
	v_mov_b32_e32 v8, v137
	v_mul_f32_e32 v10, v11, v8
	v_and_b32_e32 v11, 0x7fffffff, v10
	v_cmp_nlt_f32_e64 s[0:1], |v10|, s62
	s_and_saveexec_b64 s[10:11], s[0:1]
	s_xor_b64 s[16:17], exec, s[10:11]
	s_cbranch_execz .LBB0_108
	v_lshrrev_b32_e32 v8, 23, v11
	v_add_u32_e32 v8, 0xffffff88, v8
	v_cmp_lt_u32_e32 vcc, 63, v8
	v_mov_b32_e32 v13, v1
	v_mov_b32_e32 v15, v1
	v_cndmask_b32_e32 v9, 0, v28, vcc
	v_add_u32_e32 v8, v9, v8
	v_cmp_lt_u32_e64 s[10:11], 31, v8
	v_mov_b32_e32 v17, v1
	v_mov_b32_e32 v39, v1
	v_cndmask_b32_e64 v9, 0, v29, s[10:11]
	v_add_u32_e32 v8, v9, v8
	v_cmp_lt_u32_e64 s[12:13], 31, v8
	v_mov_b32_e32 v41, v1
	v_mov_b32_e32 v43, v1
	v_cndmask_b32_e64 v9, 0, v29, s[12:13]
	v_add_u32_e32 v37, v9, v8
	v_and_b32_e32 v8, 0x7fffff, v11
	v_or_b32_e32 v44, 0x800000, v8
	v_mad_u64_u32 v[8:9], s[0:1], v44, s63, 0
	v_mov_b32_e32 v12, v9
	v_mad_u64_u32 v[12:13], s[0:1], v44, s64, v[12:13]
	v_mov_b32_e32 v14, v13
	v_mad_u64_u32 v[14:15], s[0:1], v44, s65, v[14:15]
	v_mov_b32_e32 v16, v15
	v_mad_u64_u32 v[16:17], s[0:1], v44, s66, v[16:17]
	v_mov_b32_e32 v38, v17
	v_mad_u64_u32 v[38:39], s[0:1], v44, s67, v[38:39]
	v_mov_b32_e32 v40, v39
	v_mad_u64_u32 v[40:41], s[0:1], v44, s73, v[40:41]
	v_mov_b32_e32 v42, v41
	v_mad_u64_u32 v[42:43], s[0:1], v44, s69, v[42:43]
	v_cndmask_b32_e32 v9, v40, v16, vcc
	v_cndmask_b32_e32 v13, v42, v38, vcc
	v_cndmask_b32_e32 v17, v43, v40, vcc
	v_cndmask_b32_e64 v15, v13, v9, s[10:11]
	v_cndmask_b32_e64 v13, v17, v13, s[10:11]
	v_cndmask_b32_e32 v17, v38, v14, vcc
	v_cndmask_b32_e64 v9, v9, v17, s[10:11]
	v_cndmask_b32_e32 v12, v16, v12, vcc
	v_cndmask_b32_e64 v13, v13, v15, s[12:13]
	v_cndmask_b32_e64 v15, v15, v9, s[12:13]
	v_sub_u32_e32 v38, 32, v37
	v_cndmask_b32_e64 v16, v17, v12, s[10:11]
	v_alignbit_b32 v39, v13, v15, v38
	v_cmp_eq_u32_e64 s[14:15], 0, v37
	v_cndmask_b32_e64 v9, v9, v16, s[12:13]
	v_alignbit_b32 v17, v15, v9, v38
	v_cndmask_b32_e64 v13, v39, v13, s[14:15]
	v_cndmask_b32_e32 v8, v14, v8, vcc
	v_cndmask_b32_e64 v15, v17, v15, s[14:15]
	v_bfe_u32 v39, v13, 29, 1
	v_cndmask_b32_e64 v8, v12, v8, s[10:11]
	v_alignbit_b32 v17, v13, v15, 30
	v_sub_u32_e32 v40, 0, v39
	v_cndmask_b32_e64 v8, v16, v8, s[12:13]
	v_xor_b32_e32 v17, v17, v40
	v_alignbit_b32 v12, v9, v8, v38
	v_cndmask_b32_e64 v9, v12, v9, s[14:15]
	v_ffbh_u32_e32 v14, v17
	v_alignbit_b32 v12, v15, v9, 30
	v_min_u32_e32 v14, 32, v14
	v_alignbit_b32 v8, v9, v8, 30
	v_xor_b32_e32 v12, v12, v40
	v_sub_u32_e32 v15, 31, v14
	v_xor_b32_e32 v8, v8, v40
	v_alignbit_b32 v16, v17, v12, v15
	v_alignbit_b32 v8, v12, v8, v15
	v_alignbit_b32 v9, v16, v8, 9
	v_ffbh_u32_e32 v12, v9
	v_min_u32_e32 v12, 32, v12
	v_lshrrev_b32_e32 v37, 29, v13
	v_not_b32_e32 v15, v12
	v_alignbit_b32 v8, v9, v8, v15
	v_lshlrev_b32_e32 v9, 31, v37
	v_or_b32_e32 v15, 0x33000000, v9
	v_add_lshl_u32 v12, v12, v14, 23
	v_lshrrev_b32_e32 v8, 9, v8
	v_sub_u32_e32 v12, v15, v12
	v_or_b32_e32 v9, 0.5, v9
	v_lshlrev_b32_e32 v14, 23, v14
	v_or_b32_e32 v8, v12, v8
	v_lshrrev_b32_e32 v12, 9, v16
	v_sub_u32_e32 v9, v9, v14
	v_or_b32_e32 v9, v12, v9
	v_mul_f32_e32 v12, 0x3fc90fda, v9
	v_fma_f32 v14, v9, s70, -v12
	v_fmac_f32_e32 v14, 0x33a22168, v9
	v_fmac_f32_e32 v14, 0x3fc90fda, v8
	v_lshrrev_b32_e32 v8, 30, v13
	v_add_f32_e32 v14, v12, v14
	v_add_u32_e32 v13, v39, v8
.LBB0_108:
	s_andn2_saveexec_b64 s[10:11], s[16:17]
	v_mul_f32_e64 v8, |v10|, s71
	v_rndne_f32_e32 v8, v8
	v_cvt_i32_f32_e32 v13, v8
	v_fma_f32 v14, v8, s72, |v10|
	v_fmac_f32_e32 v14, 0xb3a22168, v8
	v_fmac_f32_e32 v14, 0xa7c234c4, v8
	s_or_b64 exec, exec, s[10:11]
	global_load_dword v12, v0, s[44:45]
	v_mul_f32_e32 v15, v14, v14
	v_fmamk_f32 v16, v15, 0xb94c1982, v23
	v_fmaak_f32 v16, v15, v16, 0xbe2aaa9d
	v_mul_f32_e32 v16, v15, v16
	v_fmac_f32_e32 v14, v14, v16
	v_fmamk_f32 v16, v15, 0x37d75334, v25
	v_fmaak_f32 v16, v15, v16, 0x3d2aabf7
	v_fmaak_f32 v16, v15, v16, 0xbf000004
	v_fma_f32 v15, v15, v16, 1.0
	v_and_b32_e32 v16, 1, v13
	v_lshlrev_b32_e32 v13, 30, v13
	v_cmp_eq_u32_e32 vcc, 0, v16
	v_and_b32_e32 v13, 0x80000000, v13
	v_xor_b32_e32 v11, v11, v10
	v_cndmask_b32_e32 v14, v15, v14, vcc
	v_xor_b32_e32 v11, v11, v13
	v_xor_b32_e32 v11, v11, v14
	v_cmp_class_f32_e64 vcc, v10, s76
	v_lshl_add_u64 v[8:9], s[46:47], 0, v[0:1]
	s_mov_b32 s0, 0
	v_cndmask_b32_e32 v13, v31, v11, vcc
	v_lshl_add_u64 v[10:11], v[4:5], 0, s[42:43]
	s_waitcnt vmcnt(0)
	ds_bpermute_b32 v208, v36, v13 offset:0
	ds_bpermute_b32 v209, v36, v13 offset:4
	ds_bpermute_b32 v210, v36, v13 offset:8
	ds_bpermute_b32 v211, v36, v13 offset:12
	ds_bpermute_b32 v212, v36, v13 offset:16
	ds_bpermute_b32 v213, v36, v13 offset:20
	ds_bpermute_b32 v214, v36, v13 offset:24
	ds_bpermute_b32 v215, v36, v13 offset:28
	s_waitcnt lgkmcnt(7)
	v_fmac_f32_e32 v12, v140, v208
	s_waitcnt lgkmcnt(6)
	v_fmac_f32_e32 v12, v141, v209
	s_waitcnt lgkmcnt(5)
	v_fmac_f32_e32 v12, v142, v210
	s_waitcnt lgkmcnt(4)
	v_fmac_f32_e32 v12, v143, v211
	s_waitcnt lgkmcnt(3)
	v_fmac_f32_e32 v12, v144, v212
	s_waitcnt lgkmcnt(2)
	v_fmac_f32_e32 v12, v145, v213
	s_waitcnt lgkmcnt(1)
	v_fmac_f32_e32 v12, v146, v214
	s_waitcnt lgkmcnt(0)
	v_fmac_f32_e32 v12, v147, v215
	ds_bpermute_b32 v208, v36, v13 offset:32
	ds_bpermute_b32 v209, v36, v13 offset:36
	ds_bpermute_b32 v210, v36, v13 offset:40
	ds_bpermute_b32 v211, v36, v13 offset:44
	ds_bpermute_b32 v212, v36, v13 offset:48
	ds_bpermute_b32 v213, v36, v13 offset:52
	ds_bpermute_b32 v214, v36, v13 offset:56
	ds_bpermute_b32 v215, v36, v13 offset:60
	s_waitcnt lgkmcnt(7)
	v_fmac_f32_e32 v12, v148, v208
	s_waitcnt lgkmcnt(6)
	v_fmac_f32_e32 v12, v149, v209
	s_waitcnt lgkmcnt(5)
	v_fmac_f32_e32 v12, v150, v210
	s_waitcnt lgkmcnt(4)
	v_fmac_f32_e32 v12, v151, v211
	s_waitcnt lgkmcnt(3)
	v_fmac_f32_e32 v12, v152, v212
	s_waitcnt lgkmcnt(2)
	v_fmac_f32_e32 v12, v153, v213
	s_waitcnt lgkmcnt(1)
	v_fmac_f32_e32 v12, v154, v214
	s_waitcnt lgkmcnt(0)
	v_fmac_f32_e32 v12, v155, v215
	ds_bpermute_b32 v208, v36, v13 offset:64
	ds_bpermute_b32 v209, v36, v13 offset:68
	ds_bpermute_b32 v210, v36, v13 offset:72
	ds_bpermute_b32 v211, v36, v13 offset:76
	ds_bpermute_b32 v212, v36, v13 offset:80
	ds_bpermute_b32 v213, v36, v13 offset:84
	ds_bpermute_b32 v214, v36, v13 offset:88
	ds_bpermute_b32 v215, v36, v13 offset:92
	s_waitcnt lgkmcnt(7)
	v_fmac_f32_e32 v12, v156, v208
	s_waitcnt lgkmcnt(6)
	v_fmac_f32_e32 v12, v157, v209
	s_waitcnt lgkmcnt(5)
	v_fmac_f32_e32 v12, v158, v210
	s_waitcnt lgkmcnt(4)
	v_fmac_f32_e32 v12, v159, v211
	s_waitcnt lgkmcnt(3)
	v_fmac_f32_e32 v12, v160, v212
	s_waitcnt lgkmcnt(2)
	v_fmac_f32_e32 v12, v161, v213
	s_waitcnt lgkmcnt(1)
	v_fmac_f32_e32 v12, v162, v214
	s_waitcnt lgkmcnt(0)
	v_fmac_f32_e32 v12, v163, v215
	ds_bpermute_b32 v208, v36, v13 offset:96
	ds_bpermute_b32 v209, v36, v13 offset:100
	ds_bpermute_b32 v210, v36, v13 offset:104
	ds_bpermute_b32 v211, v36, v13 offset:108
	ds_bpermute_b32 v212, v36, v13 offset:112
	ds_bpermute_b32 v213, v36, v13 offset:116
	ds_bpermute_b32 v214, v36, v13 offset:120
	ds_bpermute_b32 v215, v36, v13 offset:124
	s_waitcnt lgkmcnt(7)
	v_fmac_f32_e32 v12, v164, v208
	s_waitcnt lgkmcnt(6)
	v_fmac_f32_e32 v12, v165, v209
	s_waitcnt lgkmcnt(5)
	v_fmac_f32_e32 v12, v166, v210
	s_waitcnt lgkmcnt(4)
	v_fmac_f32_e32 v12, v167, v211
	s_waitcnt lgkmcnt(3)
	v_fmac_f32_e32 v12, v168, v212
	s_waitcnt lgkmcnt(2)
	v_fmac_f32_e32 v12, v169, v213
	s_waitcnt lgkmcnt(1)
	v_fmac_f32_e32 v12, v170, v214
	s_waitcnt lgkmcnt(0)
	v_fmac_f32_e32 v12, v171, v215
	ds_bpermute_b32 v208, v36, v13 offset:128
	ds_bpermute_b32 v209, v36, v13 offset:132
	ds_bpermute_b32 v210, v36, v13 offset:136
	ds_bpermute_b32 v211, v36, v13 offset:140
	ds_bpermute_b32 v212, v36, v13 offset:144
	ds_bpermute_b32 v213, v36, v13 offset:148
	ds_bpermute_b32 v214, v36, v13 offset:152
	ds_bpermute_b32 v215, v36, v13 offset:156
	s_waitcnt lgkmcnt(7)
	v_fmac_f32_e32 v12, v172, v208
	s_waitcnt lgkmcnt(6)
	v_fmac_f32_e32 v12, v173, v209
	s_waitcnt lgkmcnt(5)
	v_fmac_f32_e32 v12, v174, v210
	s_waitcnt lgkmcnt(4)
	v_fmac_f32_e32 v12, v175, v211
	s_waitcnt lgkmcnt(3)
	v_fmac_f32_e32 v12, v176, v212
	s_waitcnt lgkmcnt(2)
	v_fmac_f32_e32 v12, v177, v213
	s_waitcnt lgkmcnt(1)
	v_fmac_f32_e32 v12, v178, v214
	s_waitcnt lgkmcnt(0)
	v_fmac_f32_e32 v12, v179, v215
	ds_bpermute_b32 v208, v36, v13 offset:160
	ds_bpermute_b32 v209, v36, v13 offset:164
	ds_bpermute_b32 v210, v36, v13 offset:168
	ds_bpermute_b32 v211, v36, v13 offset:172
	ds_bpermute_b32 v212, v36, v13 offset:176
	ds_bpermute_b32 v213, v36, v13 offset:180
	ds_bpermute_b32 v214, v36, v13 offset:184
	ds_bpermute_b32 v215, v36, v13 offset:188
	s_waitcnt lgkmcnt(7)
	v_fmac_f32_e32 v12, v180, v208
	s_waitcnt lgkmcnt(6)
	v_fmac_f32_e32 v12, v181, v209
	s_waitcnt lgkmcnt(5)
	v_fmac_f32_e32 v12, v182, v210
	s_waitcnt lgkmcnt(4)
	v_fmac_f32_e32 v12, v183, v211
	s_waitcnt lgkmcnt(3)
	v_fmac_f32_e32 v12, v184, v212
	s_waitcnt lgkmcnt(2)
	v_fmac_f32_e32 v12, v185, v213
	s_waitcnt lgkmcnt(1)
	v_fmac_f32_e32 v12, v186, v214
	s_waitcnt lgkmcnt(0)
	v_fmac_f32_e32 v12, v187, v215
	ds_bpermute_b32 v208, v36, v13 offset:192
	ds_bpermute_b32 v209, v36, v13 offset:196
	ds_bpermute_b32 v210, v36, v13 offset:200
	ds_bpermute_b32 v211, v36, v13 offset:204
	ds_bpermute_b32 v212, v36, v13 offset:208
	ds_bpermute_b32 v213, v36, v13 offset:212
	ds_bpermute_b32 v214, v36, v13 offset:216
	ds_bpermute_b32 v215, v36, v13 offset:220
	s_waitcnt lgkmcnt(7)
	v_fmac_f32_e32 v12, v188, v208
	s_waitcnt lgkmcnt(6)
	v_fmac_f32_e32 v12, v189, v209
	s_waitcnt lgkmcnt(5)
	v_fmac_f32_e32 v12, v190, v210
	s_waitcnt lgkmcnt(4)
	v_fmac_f32_e32 v12, v191, v211
	s_waitcnt lgkmcnt(3)
	v_fmac_f32_e32 v12, v192, v212
	s_waitcnt lgkmcnt(2)
	v_fmac_f32_e32 v12, v193, v213
	s_waitcnt lgkmcnt(1)
	v_fmac_f32_e32 v12, v194, v214
	s_waitcnt lgkmcnt(0)
	v_fmac_f32_e32 v12, v195, v215
	ds_bpermute_b32 v208, v36, v13 offset:224
	ds_bpermute_b32 v209, v36, v13 offset:228
	ds_bpermute_b32 v210, v36, v13 offset:232
	ds_bpermute_b32 v211, v36, v13 offset:236
	ds_bpermute_b32 v212, v36, v13 offset:240
	ds_bpermute_b32 v213, v36, v13 offset:244
	ds_bpermute_b32 v214, v36, v13 offset:248
	ds_bpermute_b32 v215, v36, v13 offset:252
	s_waitcnt lgkmcnt(7)
	v_fmac_f32_e32 v12, v196, v208
	s_waitcnt lgkmcnt(6)
	v_fmac_f32_e32 v12, v197, v209
	s_waitcnt lgkmcnt(5)
	v_fmac_f32_e32 v12, v198, v210
	s_waitcnt lgkmcnt(4)
	v_fmac_f32_e32 v12, v199, v211
	s_waitcnt lgkmcnt(3)
	v_fmac_f32_e32 v12, v200, v212
	s_waitcnt lgkmcnt(2)
	v_fmac_f32_e32 v12, v201, v213
	s_waitcnt lgkmcnt(1)
	v_fmac_f32_e32 v12, v202, v214
	s_waitcnt lgkmcnt(0)
	v_fmac_f32_e32 v12, v203, v215
	v_mov_b32_e32 v8, v138
	v_mul_f32_e32 v8, v12, v8
	v_and_b32_e32 v9, 0x7fffffff, v8
	v_cmp_nlt_f32_e64 s[0:1], |v8|, s62
	s_and_saveexec_b64 s[10:11], s[0:1]
	s_xor_b64 s[16:17], exec, s[10:11]
	s_cbranch_execz .LBB0_114
	v_lshrrev_b32_e32 v10, 23, v9
	v_add_u32_e32 v10, 0xffffff88, v10
	v_cmp_lt_u32_e32 vcc, 63, v10
	v_mov_b32_e32 v13, v1
	v_mov_b32_e32 v15, v1
	v_cndmask_b32_e32 v11, 0, v28, vcc
	v_add_u32_e32 v10, v11, v10
	v_cmp_lt_u32_e64 s[10:11], 31, v10
	v_mov_b32_e32 v17, v1
	v_mov_b32_e32 v39, v1
	v_cndmask_b32_e64 v11, 0, v29, s[10:11]
	v_add_u32_e32 v10, v11, v10
	v_cmp_lt_u32_e64 s[12:13], 31, v10
	v_mov_b32_e32 v41, v1
	v_mov_b32_e32 v43, v1
	v_cndmask_b32_e64 v11, 0, v29, s[12:13]
	v_add_u32_e32 v37, v11, v10
	v_and_b32_e32 v10, 0x7fffff, v9
	v_or_b32_e32 v44, 0x800000, v10
	v_mad_u64_u32 v[10:11], s[0:1], v44, s63, 0
	v_mov_b32_e32 v12, v11
	v_mad_u64_u32 v[12:13], s[0:1], v44, s64, v[12:13]
	v_mov_b32_e32 v14, v13
	v_mad_u64_u32 v[14:15], s[0:1], v44, s65, v[14:15]
	v_mov_b32_e32 v16, v15
	v_mad_u64_u32 v[16:17], s[0:1], v44, s66, v[16:17]
	v_mov_b32_e32 v38, v17
	v_mad_u64_u32 v[38:39], s[0:1], v44, s67, v[38:39]
	v_mov_b32_e32 v40, v39
	v_mad_u64_u32 v[40:41], s[0:1], v44, s73, v[40:41]
	v_mov_b32_e32 v42, v41
	v_mad_u64_u32 v[42:43], s[0:1], v44, s69, v[42:43]
	v_cndmask_b32_e32 v11, v40, v16, vcc
	v_cndmask_b32_e32 v13, v42, v38, vcc
	v_cndmask_b32_e32 v17, v43, v40, vcc
	v_cndmask_b32_e64 v15, v13, v11, s[10:11]
	v_cndmask_b32_e64 v13, v17, v13, s[10:11]
	v_cndmask_b32_e32 v17, v38, v14, vcc
	v_cndmask_b32_e64 v11, v11, v17, s[10:11]
	v_cndmask_b32_e32 v12, v16, v12, vcc
	v_cndmask_b32_e64 v13, v13, v15, s[12:13]
	v_cndmask_b32_e64 v15, v15, v11, s[12:13]
	v_sub_u32_e32 v38, 32, v37
	v_cndmask_b32_e64 v16, v17, v12, s[10:11]
	v_alignbit_b32 v39, v13, v15, v38
	v_cmp_eq_u32_e64 s[14:15], 0, v37
	v_cndmask_b32_e64 v11, v11, v16, s[12:13]
	v_alignbit_b32 v17, v15, v11, v38
	v_cndmask_b32_e64 v13, v39, v13, s[14:15]
	v_cndmask_b32_e32 v10, v14, v10, vcc
	v_cndmask_b32_e64 v15, v17, v15, s[14:15]
	v_bfe_u32 v39, v13, 29, 1
	v_cndmask_b32_e64 v10, v12, v10, s[10:11]
	v_alignbit_b32 v17, v13, v15, 30
	v_sub_u32_e32 v40, 0, v39
	v_cndmask_b32_e64 v10, v16, v10, s[12:13]
	v_xor_b32_e32 v17, v17, v40
	v_alignbit_b32 v12, v11, v10, v38
	v_cndmask_b32_e64 v11, v12, v11, s[14:15]
	v_ffbh_u32_e32 v14, v17
	v_alignbit_b32 v12, v15, v11, 30
	v_min_u32_e32 v14, 32, v14
	v_alignbit_b32 v10, v11, v10, 30
	v_xor_b32_e32 v12, v12, v40
	v_sub_u32_e32 v15, 31, v14
	v_xor_b32_e32 v10, v10, v40
	v_alignbit_b32 v16, v17, v12, v15
	v_alignbit_b32 v10, v12, v10, v15
	v_alignbit_b32 v11, v16, v10, 9
	v_ffbh_u32_e32 v12, v11
	v_min_u32_e32 v12, 32, v12
	v_lshrrev_b32_e32 v37, 29, v13
	v_not_b32_e32 v15, v12
	v_alignbit_b32 v10, v11, v10, v15
	v_lshlrev_b32_e32 v11, 31, v37
	v_or_b32_e32 v15, 0x33000000, v11
	v_add_lshl_u32 v12, v12, v14, 23
	v_lshrrev_b32_e32 v10, 9, v10
	v_sub_u32_e32 v12, v15, v12
	v_or_b32_e32 v11, 0.5, v11
	v_lshlrev_b32_e32 v14, 23, v14
	v_or_b32_e32 v10, v12, v10
	v_lshrrev_b32_e32 v12, 9, v16
	v_sub_u32_e32 v11, v11, v14
	v_or_b32_e32 v11, v12, v11
	v_mul_f32_e32 v12, 0x3fc90fda, v11
	v_fma_f32 v14, v11, s70, -v12
	v_fmac_f32_e32 v14, 0x33a22168, v11
	v_fmac_f32_e32 v14, 0x3fc90fda, v10
	v_lshrrev_b32_e32 v10, 30, v13
	v_add_f32_e32 v11, v12, v14
	v_add_u32_e32 v10, v39, v10
